# speedup vs baseline: 1.0992x; 1.0336x over previous
; #define MFMA16(a, b, c) __builtin_amdgcn_mfma_f32_16x16x32_bf16(a, b, c, 0, 0, 0)
; #define MFMA8(a, b, c) __builtin_amdgcn_mfma_f32_16x16x32_fp8_fp8(a, b, c, 0, 0, 0)
; template <bool FP8>
; __device__ __forceinline__ void gemm_tile_256(const u16* __restrict__ A, int lda, const u16* __restrict__ Bt, int ldb,
;                                               int K, char* smem, f32x4 (&acc)[8][4]) {
;     ...
; #pragma unroll
;     for (int kk = 0; kk < 2; ++kk) {
;       const int ch = ((kk * 4 + fq) ^ sw) << 4;
;       bf16x8 bfr[4], af[8];
; #pragma unroll
;       for (int n = 0; n < 4; ++n) bfr[n] = *(const bf16x8*)(smem + brow + n * 2048 + ch);
; #pragma unroll
;       for (int m = 0; m < 8; ++m) af[m] = *(const bf16x8*)(smem + arow + m * 2048 + ch);
;       __builtin_amdgcn_sched_group_barrier(0x100, 12, 0);
;       __builtin_amdgcn_sched_group_barrier(0x008, 32, 0);
; #pragma unroll
;       for (int m = 0; m < 8; ++m)
; #pragma unroll
;         for (int n = 0; n < 4; ++n) {
;           if (FP8) {
;             union { bf16x8 v; long l[2]; } ua, ub;
;             ua.v = af[m]; ub.v = bfr[n];
;             acc[m][n] = MFMA8(ub.l[0], ua.l[0], acc[m][n]);
;             acc[m][n] = MFMA8(ub.l[1], ua.l[1], acc[m][n]);
;           } else {
;             acc[m][n] = MFMA16(bfr[n], af[m], acc[m][n]);
;           }
;         }
.LBB0_127:
	s_setprio 2
	v_add_u32_e32 v185, v180, v183
	ds_read_b128 v[186:189], v185 offset:32768
	ds_read_b128 v[190:193], v185 offset:34816
	ds_read_b128 v[194:197], v185 offset:36864
	ds_read_b128 v[198:201], v185 offset:38912
	v_add_u32_e32 v185, v181, v183
	ds_read_b128 v[202:205], v185
	ds_read_b128 v[206:209], v185 offset:2048
	ds_read_b128 v[210:213], v185 offset:4096
	ds_read_b128 v[224:227], v185 offset:6144
	ds_read_b128 v[236:239], v185 offset:8192
	ds_read_b128 v[240:243], v185 offset:10240
	ds_read_b128 v[244:247], v185 offset:12288
	ds_read_b128 v[248:251], v185 offset:14336
	v_add_u32_e32 v185, v180, v184
	s_waitcnt lgkmcnt(7)
	v_mfma_f32_16x16x32_bf16 v[112:115], v[198:201], v[202:205], v[112:115]
	s_add_u32 s10, s10, 0x80
	s_addc_u32 s11, s11, 0
	s_add_i32 s5, s5, 1
	s_waitcnt lgkmcnt(6)
	v_mfma_f32_16x16x32_bf16 v[96:99], v[198:201], v[206:209], v[96:99]
	s_cmpk_lg_i32 s10, 0x1000
	s_waitcnt lgkmcnt(5)
	v_mfma_f32_16x16x32_bf16 v[80:83], v[198:201], v[210:213], v[80:83]
	s_waitcnt lgkmcnt(4)
	v_mfma_f32_16x16x32_bf16 v[64:67], v[198:201], v[224:227], v[64:67]
	s_waitcnt lgkmcnt(3)
	v_mfma_f32_16x16x32_bf16 v[48:51], v[198:201], v[236:239], v[48:51]
	s_waitcnt lgkmcnt(2)
	v_mfma_f32_16x16x32_bf16 v[32:35], v[198:201], v[240:243], v[32:35]
	s_waitcnt lgkmcnt(1)
	v_mfma_f32_16x16x32_bf16 v[16:19], v[198:201], v[244:247], v[16:19]
	s_waitcnt lgkmcnt(0)
	v_mfma_f32_16x16x32_bf16 v[0:3], v[198:201], v[248:251], v[0:3]
	ds_read_b128 v[198:201], v185 offset:38912
	v_mfma_f32_16x16x32_bf16 v[116:119], v[194:197], v[202:205], v[116:119]
	v_mfma_f32_16x16x32_bf16 v[100:103], v[194:197], v[206:209], v[100:103]
	v_mfma_f32_16x16x32_bf16 v[84:87], v[194:197], v[210:213], v[84:87]
	v_mfma_f32_16x16x32_bf16 v[68:71], v[194:197], v[224:227], v[68:71]
	v_mfma_f32_16x16x32_bf16 v[52:55], v[194:197], v[236:239], v[52:55]
	v_mfma_f32_16x16x32_bf16 v[36:39], v[194:197], v[240:243], v[36:39]
	v_mfma_f32_16x16x32_bf16 v[20:23], v[194:197], v[244:247], v[20:23]
	v_mfma_f32_16x16x32_bf16 v[4:7], v[194:197], v[248:251], v[4:7]
	ds_read_b128 v[194:197], v185 offset:36864
	v_mfma_f32_16x16x32_bf16 v[120:123], v[190:193], v[202:205], v[120:123]
	v_mfma_f32_16x16x32_bf16 v[104:107], v[190:193], v[206:209], v[104:107]
	v_mfma_f32_16x16x32_bf16 v[88:91], v[190:193], v[210:213], v[88:91]
	v_mfma_f32_16x16x32_bf16 v[72:75], v[190:193], v[224:227], v[72:75]
	v_mfma_f32_16x16x32_bf16 v[56:59], v[190:193], v[236:239], v[56:59]
	v_mfma_f32_16x16x32_bf16 v[40:43], v[190:193], v[240:243], v[40:43]
	v_mfma_f32_16x16x32_bf16 v[24:27], v[190:193], v[244:247], v[24:27]
	v_mfma_f32_16x16x32_bf16 v[8:11], v[190:193], v[248:251], v[8:11]
	ds_read_b128 v[190:193], v185 offset:34816
	v_mfma_f32_16x16x32_bf16 v[124:127], v[186:189], v[202:205], v[124:127]
	v_mfma_f32_16x16x32_bf16 v[108:111], v[186:189], v[206:209], v[108:111]
	v_mfma_f32_16x16x32_bf16 v[92:95], v[186:189], v[210:213], v[92:95]
	v_mfma_f32_16x16x32_bf16 v[76:79], v[186:189], v[224:227], v[76:79]
	v_mfma_f32_16x16x32_bf16 v[60:63], v[186:189], v[236:239], v[60:63]
	v_mfma_f32_16x16x32_bf16 v[44:47], v[186:189], v[240:243], v[44:47]
	v_mfma_f32_16x16x32_bf16 v[28:31], v[186:189], v[244:247], v[28:31]
	v_mfma_f32_16x16x32_bf16 v[12:15], v[186:189], v[248:251], v[12:15]
	ds_read_b128 v[186:189], v185 offset:32768
	v_add_u32_e32 v185, v181, v184
	ds_read_b128 v[202:205], v185
	ds_read_b128 v[206:209], v185 offset:2048
	ds_read_b128 v[210:213], v185 offset:4096
	ds_read_b128 v[224:227], v185 offset:6144
	ds_read_b128 v[236:239], v185 offset:8192
	ds_read_b128 v[240:243], v185 offset:10240
	ds_read_b128 v[244:247], v185 offset:12288
	ds_read_b128 v[248:251], v185 offset:14336
	s_waitcnt lgkmcnt(7)
	v_mfma_f32_16x16x32_bf16 v[124:127], v[186:189], v[202:205], v[124:127]
	v_mfma_f32_16x16x32_bf16 v[120:123], v[190:193], v[202:205], v[120:123]
	v_mfma_f32_16x16x32_bf16 v[116:119], v[194:197], v[202:205], v[116:119]
	v_mfma_f32_16x16x32_bf16 v[112:115], v[198:201], v[202:205], v[112:115]
	s_waitcnt lgkmcnt(6)
	v_mfma_f32_16x16x32_bf16 v[108:111], v[186:189], v[206:209], v[108:111]
	v_mfma_f32_16x16x32_bf16 v[104:107], v[190:193], v[206:209], v[104:107]
	v_mfma_f32_16x16x32_bf16 v[100:103], v[194:197], v[206:209], v[100:103]
	v_mfma_f32_16x16x32_bf16 v[96:99], v[198:201], v[206:209], v[96:99]
	s_waitcnt lgkmcnt(5)
	v_mfma_f32_16x16x32_bf16 v[92:95], v[186:189], v[210:213], v[92:95]
	v_mfma_f32_16x16x32_bf16 v[88:91], v[190:193], v[210:213], v[88:91]
	v_mfma_f32_16x16x32_bf16 v[84:87], v[194:197], v[210:213], v[84:87]
	v_mfma_f32_16x16x32_bf16 v[80:83], v[198:201], v[210:213], v[80:83]
	s_waitcnt lgkmcnt(4)
	v_mfma_f32_16x16x32_bf16 v[76:79], v[186:189], v[224:227], v[76:79]
	v_mfma_f32_16x16x32_bf16 v[72:75], v[190:193], v[224:227], v[72:75]
	v_mfma_f32_16x16x32_bf16 v[68:71], v[194:197], v[224:227], v[68:71]
	v_mfma_f32_16x16x32_bf16 v[64:67], v[198:201], v[224:227], v[64:67]
	s_waitcnt lgkmcnt(3)
	v_mfma_f32_16x16x32_bf16 v[60:63], v[186:189], v[236:239], v[60:63]
	v_mfma_f32_16x16x32_bf16 v[56:59], v[190:193], v[236:239], v[56:59]
	v_mfma_f32_16x16x32_bf16 v[52:55], v[194:197], v[236:239], v[52:55]
	v_mfma_f32_16x16x32_bf16 v[48:51], v[198:201], v[236:239], v[48:51]
	s_waitcnt lgkmcnt(2)
	v_mfma_f32_16x16x32_bf16 v[44:47], v[186:189], v[240:243], v[44:47]
	v_mfma_f32_16x16x32_bf16 v[40:43], v[190:193], v[240:243], v[40:43]
	v_mfma_f32_16x16x32_bf16 v[36:39], v[194:197], v[240:243], v[36:39]
	v_mfma_f32_16x16x32_bf16 v[32:35], v[198:201], v[240:243], v[32:35]
	s_waitcnt lgkmcnt(1)
	v_mfma_f32_16x16x32_bf16 v[28:31], v[186:189], v[244:247], v[28:31]
	v_mfma_f32_16x16x32_bf16 v[24:27], v[190:193], v[244:247], v[24:27]
	v_mfma_f32_16x16x32_bf16 v[20:23], v[194:197], v[244:247], v[20:23]
	v_mfma_f32_16x16x32_bf16 v[16:19], v[198:201], v[244:247], v[16:19]
	s_waitcnt lgkmcnt(0)
	v_mfma_f32_16x16x32_bf16 v[12:15], v[186:189], v[248:251], v[12:15]
	v_mfma_f32_16x16x32_bf16 v[8:11], v[190:193], v[248:251], v[8:11]
	v_mfma_f32_16x16x32_bf16 v[4:7], v[194:197], v[248:251], v[4:7]
	v_mfma_f32_16x16x32_bf16 v[0:3], v[198:201], v[248:251], v[0:3]
	s_cbranch_scc0 .LBB0_130
; template <bool FP8>
; __device__ __forceinline__ void gemm_tile_256(const u16* __restrict__ A, int lda, const u16* __restrict__ Bt, int ldb,
;                                               int K, char* smem, f32x4 (&acc)[8][4]) {
;     ...
;   for (int kt = 0; kt < nk; ++kt) {
;     __syncthreads();
; #pragma unroll
;     for (int q = 0; q < 8; ++q) *(u32x4*)(smem + wofs + q * 4096) = ra[q];
; #pragma unroll
;     for (int q = 0; q < 4; ++q) *(u32x4*)(smem + 32768 + wofs + q * 4096) = rb[q];
;     __syncthreads();
;     if (kt + 1 < nk) {
;       const int k0 = (kt + 1) << 6;
; #pragma unroll
;       for (int q = 0; q < 8; ++q) ra[q] = *(const u32x4*)(ag + (size_t)q * 32 * lda + k0);
; #pragma unroll
;       for (int q = 0; q < 4; ++q) rb[q] = *(const u32x4*)(bg + (size_t)q * 32 * ldb + k0);
;     }
.LBB0_128:
	s_cmp_gt_u32 s5, 30
	s_setprio 0
	s_barrier
	s_waitcnt vmcnt(0)
	ds_write_b128 v182, v[128:131]
	ds_write_b128 v182, v[132:135] offset:4096
	ds_write_b128 v182, v[148:151] offset:8192
	ds_write_b128 v182, v[136:139] offset:12288
	ds_write_b128 v182, v[152:155] offset:16384
	ds_write_b128 v182, v[144:147] offset:20480
	ds_write_b128 v182, v[156:159] offset:24576
	ds_write_b128 v182, v[140:143] offset:28672
	ds_write_b128 v182, v[172:175] offset:32768
	ds_write_b128 v182, v[168:171] offset:36864
	ds_write_b128 v182, v[164:167] offset:40960
	ds_write_b128 v182, v[160:163] offset:45056
	s_waitcnt lgkmcnt(0)
	s_barrier
	s_cbranch_scc1 .LBB0_127
	v_lshl_add_u64 v[140:141], v[176:177], 0, s[10:11]
	v_add_co_u32_e32 v128, vcc, 0x4c00000, v140
	v_lshl_add_u64 v[160:161], v[178:179], 0, s[10:11]
	s_nop 0
	v_addc_co_u32_e32 v129, vcc, 0, v141, vcc
	v_add_co_u32_e32 v132, vcc, 0x4c20000, v140
	s_nop 1
	v_addc_co_u32_e32 v133, vcc, 0, v141, vcc
	v_add_co_u32_e32 v136, vcc, 0x4c40000, v140
	global_load_dwordx4 v[128:131], v[128:129], off offset:128
	s_nop 0
	global_load_dwordx4 v[132:135], v[132:133], off offset:128
	v_addc_co_u32_e32 v137, vcc, 0, v141, vcc
	v_add_co_u32_e32 v138, vcc, 0x4c60000, v140
	s_nop 1
	v_addc_co_u32_e32 v139, vcc, 0, v141, vcc
	v_add_co_u32_e32 v142, vcc, 0x4c80000, v140
	global_load_dwordx4 v[148:151], v[136:137], off offset:128
	s_nop 0
	global_load_dwordx4 v[136:139], v[138:139], off offset:128
	v_addc_co_u32_e32 v143, vcc, 0, v141, vcc
	v_add_co_u32_e32 v144, vcc, 0x4ca0000, v140
	s_nop 1
	v_addc_co_u32_e32 v145, vcc, 0, v141, vcc
	global_load_dwordx4 v[152:155], v[142:143], off offset:128
	s_nop 0
	global_load_dwordx4 v[144:147], v[144:145], off offset:128
	v_add_co_u32_e32 v142, vcc, 0x4cc0000, v140
	s_nop 1
	v_addc_co_u32_e32 v143, vcc, 0, v141, vcc
	v_add_co_u32_e32 v140, vcc, 0x4ce0000, v140
	s_nop 1
	v_addc_co_u32_e32 v141, vcc, 0, v141, vcc
	v_add_co_u32_e32 v162, vcc, 0x400000, v160
	global_load_dwordx4 v[156:159], v[142:143], off offset:128
	s_nop 0
	global_load_dwordx4 v[140:143], v[140:141], off offset:128
	v_addc_co_u32_e32 v163, vcc, 0, v161, vcc
	v_add_co_u32_e32 v164, vcc, 0x420000, v160
	s_nop 1
	v_addc_co_u32_e32 v165, vcc, 0, v161, vcc
	global_load_dwordx4 v[172:175], v[162:163], off offset:128
	global_load_dwordx4 v[168:171], v[164:165], off offset:128
	v_add_co_u32_e32 v162, vcc, 0x440000, v160
	s_nop 1
	v_addc_co_u32_e32 v163, vcc, 0, v161, vcc
	v_add_co_u32_e32 v160, vcc, 0x460000, v160
	s_nop 1
	v_addc_co_u32_e32 v161, vcc, 0, v161, vcc
	global_load_dwordx4 v[164:167], v[162:163], off offset:128
	s_nop 0
	global_load_dwordx4 v[160:163], v[160:161], off offset:128
	s_branch .LBB0_127

; #define MFMA8(a, b, c) __builtin_amdgcn_mfma_f32_16x16x32_fp8_fp8(a, b, c, 0, 0, 0)
; template <bool FP8>
; __device__ __forceinline__ void gemm_tile_256(const u16* __restrict__ A, int lda, const u16* __restrict__ Bt, int ldb,
;                                               int K, char* smem, f32x4 (&acc)[8][4]) {
;     ...
; #pragma unroll
;     for (int kk = 0; kk < 2; ++kk) {
;       const int ch = ((kk * 4 + fq) ^ sw) << 4;
;       bf16x8 bfr[4], af[8];
; #pragma unroll
;       for (int n = 0; n < 4; ++n) bfr[n] = *(const bf16x8*)(smem + brow + n * 2048 + ch);
; #pragma unroll
;       for (int m = 0; m < 8; ++m) af[m] = *(const bf16x8*)(smem + arow + m * 2048 + ch);
;       __builtin_amdgcn_sched_group_barrier(0x100, 12, 0);
;       __builtin_amdgcn_sched_group_barrier(0x008, 32, 0);
; #pragma unroll
;       for (int m = 0; m < 8; ++m)
; #pragma unroll
;         for (int n = 0; n < 4; ++n) {
;           if (FP8) {
;             union { bf16x8 v; long l[2]; } ua, ub;
;             ua.v = af[m]; ub.v = bfr[n];
;             acc[m][n] = MFMA8(ub.l[0], ua.l[0], acc[m][n]);
;             acc[m][n] = MFMA8(ub.l[1], ua.l[1], acc[m][n]);
.LBB0_133:
	s_setprio 2
	v_add_u32_e32 v188, v237, v238
	ds_read_b128 v[176:179], v188 offset:32768
	ds_read_b128 v[180:183], v188 offset:34816
	ds_read_b128 v[184:187], v188 offset:36864
	ds_read_b128 v[188:191], v188 offset:38912
	v_add_u32_e32 v220, v236, v238
	ds_read_b128 v[208:211], v220 offset:8192
	ds_read_b128 v[212:215], v220 offset:10240
	ds_read_b128 v[240:243], v220 offset:12288
	ds_read_b128 v[244:247], v220 offset:14336
	ds_read_b128 v[192:195], v220
	ds_read_b128 v[196:199], v220 offset:2048
	ds_read_b128 v[200:203], v220 offset:4096
	ds_read_b128 v[204:207], v220 offset:6144
	s_waitcnt lgkmcnt(7)
	v_mfma_f32_16x16x32_fp8_fp8 v[60:63], v[176:177], v[208:209], v[60:63]
	s_add_u32 s10, s10, 0x80
	s_addc_u32 s11, s11, 0
	s_cmpk_lg_i32 s10, 0x800
	v_mfma_f32_16x16x32_fp8_fp8 v[56:59], v[180:181], v[208:209], v[56:59]
	v_mfma_f32_16x16x32_fp8_fp8 v[52:55], v[184:185], v[208:209], v[52:55]
	v_mfma_f32_16x16x32_fp8_fp8 v[48:51], v[188:189], v[208:209], v[48:51]
	s_waitcnt lgkmcnt(6)
	v_mfma_f32_16x16x32_fp8_fp8 v[44:47], v[176:177], v[212:213], v[44:47]
	v_mfma_f32_16x16x32_fp8_fp8 v[40:43], v[180:181], v[212:213], v[40:43]
	v_mfma_f32_16x16x32_fp8_fp8 v[36:39], v[184:185], v[212:213], v[36:39]
	v_mfma_f32_16x16x32_fp8_fp8 v[32:35], v[188:189], v[212:213], v[32:35]
	s_waitcnt lgkmcnt(5)
	v_mfma_f32_16x16x32_fp8_fp8 v[28:31], v[176:177], v[240:241], v[28:31]
	v_mfma_f32_16x16x32_fp8_fp8 v[24:27], v[180:181], v[240:241], v[24:27]
	v_mfma_f32_16x16x32_fp8_fp8 v[20:23], v[184:185], v[240:241], v[20:23]
	v_mfma_f32_16x16x32_fp8_fp8 v[16:19], v[188:189], v[240:241], v[16:19]
	s_waitcnt lgkmcnt(4)
	v_mfma_f32_16x16x32_fp8_fp8 v[12:15], v[176:177], v[244:245], v[12:15]
	v_mfma_f32_16x16x32_fp8_fp8 v[8:11], v[180:181], v[244:245], v[8:11]
	v_mfma_f32_16x16x32_fp8_fp8 v[4:7], v[184:185], v[244:245], v[4:7]
	v_mfma_f32_16x16x32_fp8_fp8 v[0:3], v[188:189], v[244:245], v[0:3]
	s_waitcnt lgkmcnt(3)
	v_mfma_f32_16x16x32_fp8_fp8 v[120:123], v[180:181], v[192:193], v[120:123]
	s_waitcnt lgkmcnt(2)
	v_mfma_f32_16x16x32_fp8_fp8 v[104:107], v[180:181], v[196:197], v[104:107]
	s_waitcnt lgkmcnt(1)
	v_mfma_f32_16x16x32_fp8_fp8 v[88:91], v[180:181], v[200:201], v[88:91]
	s_waitcnt lgkmcnt(0)
	v_mfma_f32_16x16x32_fp8_fp8 v[72:75], v[180:181], v[204:205], v[72:75]
	v_add_u32_e32 v180, v236, v239
	v_mfma_f32_16x16x32_fp8_fp8 v[60:63], v[178:179], v[210:211], v[60:63]
	v_mfma_f32_16x16x32_fp8_fp8 v[56:59], v[182:183], v[210:211], v[56:59]
	v_mfma_f32_16x16x32_fp8_fp8 v[52:55], v[186:187], v[210:211], v[52:55]
	v_mfma_f32_16x16x32_fp8_fp8 v[48:51], v[190:191], v[210:211], v[48:51]
	ds_read_b128 v[208:211], v180 offset:6144
	v_mfma_f32_16x16x32_fp8_fp8 v[44:47], v[178:179], v[214:215], v[44:47]
	v_mfma_f32_16x16x32_fp8_fp8 v[40:43], v[182:183], v[214:215], v[40:43]
	v_mfma_f32_16x16x32_fp8_fp8 v[36:39], v[186:187], v[214:215], v[36:39]
	v_mfma_f32_16x16x32_fp8_fp8 v[32:35], v[190:191], v[214:215], v[32:35]
	ds_read_b128 v[212:215], v180 offset:4096
	v_mfma_f32_16x16x32_fp8_fp8 v[28:31], v[178:179], v[242:243], v[28:31]
	v_mfma_f32_16x16x32_fp8_fp8 v[24:27], v[182:183], v[242:243], v[24:27]
	v_mfma_f32_16x16x32_fp8_fp8 v[20:23], v[186:187], v[242:243], v[20:23]
	v_mfma_f32_16x16x32_fp8_fp8 v[16:19], v[190:191], v[242:243], v[16:19]
	ds_read_b128 v[240:243], v180
	v_mfma_f32_16x16x32_fp8_fp8 v[12:15], v[178:179], v[246:247], v[12:15]
	v_mfma_f32_16x16x32_fp8_fp8 v[8:11], v[182:183], v[246:247], v[8:11]
	v_mfma_f32_16x16x32_fp8_fp8 v[4:7], v[186:187], v[246:247], v[4:7]
	v_mfma_f32_16x16x32_fp8_fp8 v[0:3], v[190:191], v[246:247], v[0:3]
	ds_read_b128 v[244:247], v180 offset:2048
	v_mfma_f32_16x16x32_fp8_fp8 v[76:79], v[176:177], v[204:205], v[76:79]
	v_mfma_f32_16x16x32_fp8_fp8 v[68:71], v[184:185], v[204:205], v[68:71]
	v_mfma_f32_16x16x32_fp8_fp8 v[64:67], v[188:189], v[204:205], v[64:67]
	v_mfma_f32_16x16x32_fp8_fp8 v[76:79], v[178:179], v[206:207], v[76:79]
	v_mfma_f32_16x16x32_fp8_fp8 v[72:75], v[182:183], v[206:207], v[72:75]
	v_mfma_f32_16x16x32_fp8_fp8 v[68:71], v[186:187], v[206:207], v[68:71]
	v_mfma_f32_16x16x32_fp8_fp8 v[64:67], v[190:191], v[206:207], v[64:67]
	ds_read_b128 v[204:207], v180 offset:8192
	v_mfma_f32_16x16x32_fp8_fp8 v[92:95], v[176:177], v[200:201], v[92:95]
	v_mfma_f32_16x16x32_fp8_fp8 v[84:87], v[184:185], v[200:201], v[84:87]
	v_mfma_f32_16x16x32_fp8_fp8 v[80:83], v[188:189], v[200:201], v[80:83]
	v_mfma_f32_16x16x32_fp8_fp8 v[92:95], v[178:179], v[202:203], v[92:95]
	v_mfma_f32_16x16x32_fp8_fp8 v[88:91], v[182:183], v[202:203], v[88:91]
	v_mfma_f32_16x16x32_fp8_fp8 v[84:87], v[186:187], v[202:203], v[84:87]
	v_mfma_f32_16x16x32_fp8_fp8 v[80:83], v[190:191], v[202:203], v[80:83]
	ds_read_b128 v[200:203], v180 offset:10240
	v_mfma_f32_16x16x32_fp8_fp8 v[108:111], v[176:177], v[196:197], v[108:111]
	v_mfma_f32_16x16x32_fp8_fp8 v[100:103], v[184:185], v[196:197], v[100:103]
	v_mfma_f32_16x16x32_fp8_fp8 v[96:99], v[188:189], v[196:197], v[96:99]
	v_mfma_f32_16x16x32_fp8_fp8 v[108:111], v[178:179], v[198:199], v[108:111]
	v_mfma_f32_16x16x32_fp8_fp8 v[104:107], v[182:183], v[198:199], v[104:107]
	v_mfma_f32_16x16x32_fp8_fp8 v[100:103], v[186:187], v[198:199], v[100:103]
	v_mfma_f32_16x16x32_fp8_fp8 v[96:99], v[190:191], v[198:199], v[96:99]
	ds_read_b128 v[196:199], v180 offset:12288
	v_mfma_f32_16x16x32_fp8_fp8 v[120:123], v[182:183], v[194:195], v[120:123]
	ds_read_b128 v[180:183], v180 offset:14336
	v_mfma_f32_16x16x32_fp8_fp8 v[112:115], v[188:189], v[192:193], v[112:115]
	v_mfma_f32_16x16x32_fp8_fp8 v[124:127], v[176:177], v[192:193], v[124:127]
	v_add_u32_e32 v176, v237, v239
	v_mfma_f32_16x16x32_fp8_fp8 v[112:115], v[190:191], v[194:195], v[112:115]
	ds_read_b128 v[188:191], v176 offset:34816
	v_mfma_f32_16x16x32_fp8_fp8 v[116:119], v[184:185], v[192:193], v[116:119]
	v_mfma_f32_16x16x32_fp8_fp8 v[116:119], v[186:187], v[194:195], v[116:119]
	ds_read_b128 v[184:187], v176 offset:36864
	v_mfma_f32_16x16x32_fp8_fp8 v[124:127], v[178:179], v[194:195], v[124:127]
	ds_read_b128 v[192:195], v176 offset:32768
	ds_read_b128 v[176:179], v176 offset:38912
	s_waitcnt lgkmcnt(1)
; #define MFMA8(a, b, c) __builtin_amdgcn_mfma_f32_16x16x32_fp8_fp8(a, b, c, 0, 0, 0)
; template <bool FP8>
; __device__ __forceinline__ void gemm_tile_256(const u16* __restrict__ A, int lda, const u16* __restrict__ Bt, int ldb,
;                                               int K, char* smem, f32x4 (&acc)[8][4]) {
;     ...
;       for (int m = 0; m < 8; ++m)
; #pragma unroll
;         for (int n = 0; n < 4; ++n) {
;           if (FP8) {
;             union { bf16x8 v; long l[2]; } ua, ub;
;             ua.v = af[m]; ub.v = bfr[n];
;             acc[m][n] = MFMA8(ub.l[0], ua.l[0], acc[m][n]);
;             acc[m][n] = MFMA8(ub.l[1], ua.l[1], acc[m][n]);
	v_mfma_f32_16x16x32_fp8_fp8 v[124:127], v[192:193], v[240:241], v[124:127]
	v_mfma_f32_16x16x32_fp8_fp8 v[120:123], v[188:189], v[240:241], v[120:123]
	v_mfma_f32_16x16x32_fp8_fp8 v[116:119], v[184:185], v[240:241], v[116:119]
	s_waitcnt lgkmcnt(0)
	v_mfma_f32_16x16x32_fp8_fp8 v[112:115], v[176:177], v[240:241], v[112:115]
	v_mfma_f32_16x16x32_fp8_fp8 v[108:111], v[192:193], v[244:245], v[108:111]
	v_mfma_f32_16x16x32_fp8_fp8 v[104:107], v[188:189], v[244:245], v[104:107]
	v_mfma_f32_16x16x32_fp8_fp8 v[100:103], v[184:185], v[244:245], v[100:103]
	v_mfma_f32_16x16x32_fp8_fp8 v[96:99], v[176:177], v[244:245], v[96:99]
	v_mfma_f32_16x16x32_fp8_fp8 v[92:95], v[192:193], v[212:213], v[92:95]
	v_mfma_f32_16x16x32_fp8_fp8 v[88:91], v[188:189], v[212:213], v[88:91]
	v_mfma_f32_16x16x32_fp8_fp8 v[84:87], v[184:185], v[212:213], v[84:87]
	v_mfma_f32_16x16x32_fp8_fp8 v[80:83], v[176:177], v[212:213], v[80:83]
	v_mfma_f32_16x16x32_fp8_fp8 v[76:79], v[192:193], v[208:209], v[76:79]
	v_mfma_f32_16x16x32_fp8_fp8 v[72:75], v[188:189], v[208:209], v[72:75]
	v_mfma_f32_16x16x32_fp8_fp8 v[68:71], v[184:185], v[208:209], v[68:71]
	v_mfma_f32_16x16x32_fp8_fp8 v[64:67], v[176:177], v[208:209], v[64:67]
	v_mfma_f32_16x16x32_fp8_fp8 v[60:63], v[192:193], v[204:205], v[60:63]
	v_mfma_f32_16x16x32_fp8_fp8 v[56:59], v[188:189], v[204:205], v[56:59]
	v_mfma_f32_16x16x32_fp8_fp8 v[52:55], v[184:185], v[204:205], v[52:55]
	v_mfma_f32_16x16x32_fp8_fp8 v[48:51], v[176:177], v[204:205], v[48:51]
	v_mfma_f32_16x16x32_fp8_fp8 v[44:47], v[192:193], v[200:201], v[44:47]
	v_mfma_f32_16x16x32_fp8_fp8 v[40:43], v[188:189], v[200:201], v[40:43]
	v_mfma_f32_16x16x32_fp8_fp8 v[36:39], v[184:185], v[200:201], v[36:39]
	v_mfma_f32_16x16x32_fp8_fp8 v[32:35], v[176:177], v[200:201], v[32:35]
	v_mfma_f32_16x16x32_fp8_fp8 v[28:31], v[192:193], v[196:197], v[28:31]
	v_mfma_f32_16x16x32_fp8_fp8 v[24:27], v[188:189], v[196:197], v[24:27]
	v_mfma_f32_16x16x32_fp8_fp8 v[20:23], v[184:185], v[196:197], v[20:23]
	v_mfma_f32_16x16x32_fp8_fp8 v[16:19], v[176:177], v[196:197], v[16:19]
	v_mfma_f32_16x16x32_fp8_fp8 v[12:15], v[192:193], v[180:181], v[12:15]
	v_mfma_f32_16x16x32_fp8_fp8 v[8:11], v[188:189], v[180:181], v[8:11]
	v_mfma_f32_16x16x32_fp8_fp8 v[4:7], v[184:185], v[180:181], v[4:7]
	v_mfma_f32_16x16x32_fp8_fp8 v[0:3], v[176:177], v[180:181], v[0:3]
	v_mfma_f32_16x16x32_fp8_fp8 v[124:127], v[194:195], v[242:243], v[124:127]
	v_mfma_f32_16x16x32_fp8_fp8 v[120:123], v[190:191], v[242:243], v[120:123]
	v_mfma_f32_16x16x32_fp8_fp8 v[116:119], v[186:187], v[242:243], v[116:119]
	v_mfma_f32_16x16x32_fp8_fp8 v[112:115], v[178:179], v[242:243], v[112:115]
	v_mfma_f32_16x16x32_fp8_fp8 v[108:111], v[194:195], v[246:247], v[108:111]
	v_mfma_f32_16x16x32_fp8_fp8 v[104:107], v[190:191], v[246:247], v[104:107]
	v_mfma_f32_16x16x32_fp8_fp8 v[100:103], v[186:187], v[246:247], v[100:103]
	v_mfma_f32_16x16x32_fp8_fp8 v[96:99], v[178:179], v[246:247], v[96:99]
	v_mfma_f32_16x16x32_fp8_fp8 v[92:95], v[194:195], v[214:215], v[92:95]
	v_mfma_f32_16x16x32_fp8_fp8 v[88:91], v[190:191], v[214:215], v[88:91]
	v_mfma_f32_16x16x32_fp8_fp8 v[84:87], v[186:187], v[214:215], v[84:87]
	v_mfma_f32_16x16x32_fp8_fp8 v[80:83], v[178:179], v[214:215], v[80:83]
	v_mfma_f32_16x16x32_fp8_fp8 v[76:79], v[194:195], v[210:211], v[76:79]
	v_mfma_f32_16x16x32_fp8_fp8 v[72:75], v[190:191], v[210:211], v[72:75]
	v_mfma_f32_16x16x32_fp8_fp8 v[68:71], v[186:187], v[210:211], v[68:71]
	v_mfma_f32_16x16x32_fp8_fp8 v[64:67], v[178:179], v[210:211], v[64:67]
	v_mfma_f32_16x16x32_fp8_fp8 v[60:63], v[194:195], v[206:207], v[60:63]
	v_mfma_f32_16x16x32_fp8_fp8 v[56:59], v[190:191], v[206:207], v[56:59]
	v_mfma_f32_16x16x32_fp8_fp8 v[52:55], v[186:187], v[206:207], v[52:55]
	v_mfma_f32_16x16x32_fp8_fp8 v[48:51], v[178:179], v[206:207], v[48:51]
	v_mfma_f32_16x16x32_fp8_fp8 v[44:47], v[194:195], v[202:203], v[44:47]
	v_mfma_f32_16x16x32_fp8_fp8 v[40:43], v[190:191], v[202:203], v[40:43]
	v_mfma_f32_16x16x32_fp8_fp8 v[36:39], v[186:187], v[202:203], v[36:39]
	v_mfma_f32_16x16x32_fp8_fp8 v[32:35], v[178:179], v[202:203], v[32:35]
	v_mfma_f32_16x16x32_fp8_fp8 v[28:31], v[194:195], v[198:199], v[28:31]
	v_mfma_f32_16x16x32_fp8_fp8 v[24:27], v[190:191], v[198:199], v[24:27]
	v_mfma_f32_16x16x32_fp8_fp8 v[20:23], v[186:187], v[198:199], v[20:23]
	v_mfma_f32_16x16x32_fp8_fp8 v[16:19], v[178:179], v[198:199], v[16:19]
	v_mfma_f32_16x16x32_fp8_fp8 v[12:15], v[194:195], v[182:183], v[12:15]
	v_mfma_f32_16x16x32_fp8_fp8 v[8:11], v[190:191], v[182:183], v[8:11]
	v_mfma_f32_16x16x32_fp8_fp8 v[4:7], v[186:187], v[182:183], v[4:7]
	v_mfma_f32_16x16x32_fp8_fp8 v[0:3], v[178:179], v[182:183], v[0:3]
	s_cbranch_scc0 .LBB0_136
; template <bool FP8>
; __device__ __forceinline__ void gemm_tile_256(const u16* __restrict__ A, int lda, const u16* __restrict__ Bt, int ldb,
;                                               int K, char* smem, f32x4 (&acc)[8][4]) {
;     ...
;   for (int kt = 0; kt < nk; ++kt) {
;     __syncthreads();
; #pragma unroll
;     for (int q = 0; q < 8; ++q) *(u32x4*)(smem + wofs + q * 4096) = ra[q];
; #pragma unroll
;     for (int q = 0; q < 4; ++q) *(u32x4*)(smem + 32768 + wofs + q * 4096) = rb[q];
;     __syncthreads();
;     if (kt + 1 < nk) {
;       const int k0 = (kt + 1) << 6;
; #pragma unroll
;       for (int q = 0; q < 8; ++q) ra[q] = *(const u32x4*)(ag + (size_t)q * 32 * lda + k0);
; #pragma unroll
;       for (int q = 0; q < 4; ++q) rb[q] = *(const u32x4*)(bg + (size_t)q * 32 * ldb + k0);
;     }
.LBB0_134:
	s_cmpk_eq_i32 s10, 0x780
	s_setprio 0
	s_barrier
	s_waitcnt vmcnt(11)
	ds_write_b128 v235, v[128:131]
	s_waitcnt vmcnt(10)
	ds_write_b128 v235, v[132:135] offset:4096
	s_waitcnt vmcnt(9)
	ds_write_b128 v235, v[136:139] offset:8192
	s_waitcnt vmcnt(8)
	ds_write_b128 v235, v[140:143] offset:12288
	s_waitcnt vmcnt(7)
	ds_write_b128 v235, v[144:147] offset:16384
	s_waitcnt vmcnt(6)
	ds_write_b128 v235, v[148:151] offset:20480
	s_waitcnt vmcnt(5)
	ds_write_b128 v235, v[152:155] offset:24576
	s_waitcnt vmcnt(4)
	ds_write_b128 v235, v[156:159] offset:28672
	s_waitcnt vmcnt(3)
	ds_write_b128 v235, v[160:163] offset:32768
	s_waitcnt vmcnt(2)
	ds_write_b128 v235, v[164:167] offset:36864
	s_waitcnt vmcnt(1)
	ds_write_b128 v235, v[168:171] offset:40960
	s_waitcnt vmcnt(0)
	ds_write_b128 v235, v[172:175] offset:45056
	s_waitcnt lgkmcnt(0)
	s_barrier
	s_cbranch_scc1 .LBB0_133
	v_lshl_add_u64 v[152:153], v[224:225], 0, s[10:11]
	v_add_co_u32_e32 v128, vcc, 0x38c00000, v152
	v_lshl_add_u64 v[168:169], v[226:227], 0, s[10:11]
	s_nop 0
	v_addc_co_u32_e32 v129, vcc, 0, v153, vcc
	v_add_co_u32_e32 v132, vcc, 0x38c10000, v152
	s_nop 1
	v_addc_co_u32_e32 v133, vcc, 0, v153, vcc
	v_add_co_u32_e32 v136, vcc, 0x38c20000, v152
	global_load_dwordx4 v[128:131], v[128:129], off offset:128
	s_nop 0
	global_load_dwordx4 v[132:135], v[132:133], off offset:128
	v_addc_co_u32_e32 v137, vcc, 0, v153, vcc
	v_add_co_u32_e32 v140, vcc, 0x38c30000, v152
	s_nop 1
	v_addc_co_u32_e32 v141, vcc, 0, v153, vcc
	v_add_co_u32_e32 v144, vcc, 0x38c40000, v152
	global_load_dwordx4 v[136:139], v[136:137], off offset:128
	s_nop 0
	global_load_dwordx4 v[140:143], v[140:141], off offset:128
	v_addc_co_u32_e32 v145, vcc, 0, v153, vcc
	v_add_co_u32_e32 v148, vcc, 0x38c50000, v152
	s_nop 1
	v_addc_co_u32_e32 v149, vcc, 0, v153, vcc
	v_add_co_u32_e32 v154, vcc, 0x38c60000, v152
	global_load_dwordx4 v[144:147], v[144:145], off offset:128
	s_nop 0
	global_load_dwordx4 v[148:151], v[148:149], off offset:128
	v_addc_co_u32_e32 v155, vcc, 0, v153, vcc
	v_add_co_u32_e32 v156, vcc, 0x38c70000, v152
	s_nop 1
	v_addc_co_u32_e32 v157, vcc, 0, v153, vcc
	v_add_co_u32_e32 v160, vcc, 0x3cc00000, v168
	global_load_dwordx4 v[152:155], v[154:155], off offset:128
	s_nop 0
	global_load_dwordx4 v[156:159], v[156:157], off offset:128
	v_addc_co_u32_e32 v161, vcc, 0, v169, vcc
	v_add_co_u32_e32 v164, vcc, 0x3cc10000, v168
	s_nop 1
	v_addc_co_u32_e32 v165, vcc, 0, v169, vcc
	v_add_co_u32_e32 v170, vcc, 0x3cc20000, v168
	global_load_dwordx4 v[160:163], v[160:161], off offset:128
	s_nop 0
	global_load_dwordx4 v[164:167], v[164:165], off offset:128
	v_addc_co_u32_e32 v171, vcc, 0, v169, vcc
	v_add_co_u32_e32 v172, vcc, 0x3cc30000, v168
	s_nop 1
	v_addc_co_u32_e32 v173, vcc, 0, v169, vcc
	global_load_dwordx4 v[168:171], v[170:171], off offset:128
	s_nop 0
	global_load_dwordx4 v[172:175], v[172:173], off offset:128
	s_branch .LBB0_133

; #define MFMA16(a, b, c) __builtin_amdgcn_mfma_f32_16x16x32_bf16(a, b, c, 0, 0, 0)
; #define MFMA8(a, b, c) __builtin_amdgcn_mfma_f32_16x16x32_fp8_fp8(a, b, c, 0, 0, 0)
; template <bool FP8>
; __device__ __forceinline__ void gemm_tile_256(const u16* __restrict__ A, int lda, const u16* __restrict__ Bt, int ldb,
;                                               int K, char* smem, f32x4 (&acc)[8][4]) {
;     ...
; #pragma unroll
;     for (int kk = 0; kk < 2; ++kk) {
;       const int ch = ((kk * 4 + fq) ^ sw) << 4;
;       bf16x8 bfr[4], af[8];
; #pragma unroll
;       for (int n = 0; n < 4; ++n) bfr[n] = *(const bf16x8*)(smem + brow + n * 2048 + ch);
; #pragma unroll
;       for (int m = 0; m < 8; ++m) af[m] = *(const bf16x8*)(smem + arow + m * 2048 + ch);
;       __builtin_amdgcn_sched_group_barrier(0x100, 12, 0);
;       __builtin_amdgcn_sched_group_barrier(0x008, 32, 0);
; #pragma unroll
;       for (int m = 0; m < 8; ++m)
; #pragma unroll
;         for (int n = 0; n < 4; ++n) {
;           if (FP8) {
;             union { bf16x8 v; long l[2]; } ua, ub;
;             ua.v = af[m]; ub.v = bfr[n];
;             acc[m][n] = MFMA8(ub.l[0], ua.l[0], acc[m][n]);
;             acc[m][n] = MFMA8(ub.l[1], ua.l[1], acc[m][n]);
;           } else {
;             acc[m][n] = MFMA16(bfr[n], af[m], acc[m][n]);
;           }
;         }
.LBB0_950:
	s_setprio 2
	v_add_u32_e32 v178, v193, v196
	ds_read_b128 v[198:201], v178 offset:32768
	ds_read_b128 v[202:205], v178 offset:34816
	ds_read_b128 v[206:209], v178 offset:36864
	ds_read_b128 v[210:213], v178 offset:38912
	v_add_u32_e32 v178, v194, v196
	ds_read_b128 v[218:221], v178
	ds_read_b128 v[222:225], v178 offset:2048
	ds_read_b128 v[226:229], v178 offset:4096
	ds_read_b128 v[230:233], v178 offset:6144
	ds_read_b128 v[234:237], v178 offset:8192
	ds_read_b128 v[238:241], v178 offset:10240
	ds_read_b128 v[242:245], v178 offset:12288
	ds_read_b128 v[246:249], v178 offset:14336
	v_add_u32_e32 v178, v193, v197
	s_waitcnt lgkmcnt(7)
	v_mfma_f32_16x16x32_bf16 v[160:163], v[210:213], v[218:221], v[160:163]
	s_add_u32 s10, s10, 0x80
	s_addc_u32 s11, s11, 0
	s_add_i32 s7, s7, 1
	s_waitcnt lgkmcnt(6)
	v_mfma_f32_16x16x32_bf16 v[96:99], v[210:213], v[222:225], v[96:99]
	s_cmpk_lg_i32 s10, 0x800
	s_waitcnt lgkmcnt(5)
	v_mfma_f32_16x16x32_bf16 v[80:83], v[210:213], v[226:229], v[80:83]
	s_waitcnt lgkmcnt(4)
	v_mfma_f32_16x16x32_bf16 v[64:67], v[210:213], v[230:233], v[64:67]
	s_waitcnt lgkmcnt(3)
	v_mfma_f32_16x16x32_bf16 v[48:51], v[210:213], v[234:237], v[48:51]
	s_waitcnt lgkmcnt(2)
	v_mfma_f32_16x16x32_bf16 v[32:35], v[210:213], v[238:241], v[32:35]
	s_waitcnt lgkmcnt(1)
	v_mfma_f32_16x16x32_bf16 v[16:19], v[210:213], v[242:245], v[16:19]
	s_waitcnt lgkmcnt(0)
	v_mfma_f32_16x16x32_bf16 v[0:3], v[210:213], v[246:249], v[0:3]
	ds_read_b128 v[210:213], v178 offset:38912
	v_mfma_f32_16x16x32_bf16 v[164:167], v[206:209], v[218:221], v[164:167]
	v_mfma_f32_16x16x32_bf16 v[100:103], v[206:209], v[222:225], v[100:103]
	v_mfma_f32_16x16x32_bf16 v[84:87], v[206:209], v[226:229], v[84:87]
	v_mfma_f32_16x16x32_bf16 v[68:71], v[206:209], v[230:233], v[68:71]
	v_mfma_f32_16x16x32_bf16 v[52:55], v[206:209], v[234:237], v[52:55]
	v_mfma_f32_16x16x32_bf16 v[36:39], v[206:209], v[238:241], v[36:39]
	v_mfma_f32_16x16x32_bf16 v[20:23], v[206:209], v[242:245], v[20:23]
	v_mfma_f32_16x16x32_bf16 v[4:7], v[206:209], v[246:249], v[4:7]
	ds_read_b128 v[206:209], v178 offset:36864
	v_mfma_f32_16x16x32_bf16 v[168:171], v[202:205], v[218:221], v[168:171]
	v_mfma_f32_16x16x32_bf16 v[120:123], v[202:205], v[222:225], v[120:123]
	v_mfma_f32_16x16x32_bf16 v[88:91], v[202:205], v[226:229], v[88:91]
	v_mfma_f32_16x16x32_bf16 v[72:75], v[202:205], v[230:233], v[72:75]
	v_mfma_f32_16x16x32_bf16 v[56:59], v[202:205], v[234:237], v[56:59]
	v_mfma_f32_16x16x32_bf16 v[40:43], v[202:205], v[238:241], v[40:43]
	v_mfma_f32_16x16x32_bf16 v[24:27], v[202:205], v[242:245], v[24:27]
	v_mfma_f32_16x16x32_bf16 v[8:11], v[202:205], v[246:249], v[8:11]
	ds_read_b128 v[202:205], v178 offset:34816
	v_mfma_f32_16x16x32_bf16 v[172:175], v[198:201], v[218:221], v[172:175]
	v_mfma_f32_16x16x32_bf16 v[156:159], v[198:201], v[222:225], v[156:159]
	v_mfma_f32_16x16x32_bf16 v[92:95], v[198:201], v[226:229], v[92:95]
	v_mfma_f32_16x16x32_bf16 v[76:79], v[198:201], v[230:233], v[76:79]
	v_mfma_f32_16x16x32_bf16 v[60:63], v[198:201], v[234:237], v[60:63]
	v_mfma_f32_16x16x32_bf16 v[44:47], v[198:201], v[238:241], v[44:47]
	v_mfma_f32_16x16x32_bf16 v[28:31], v[198:201], v[242:245], v[28:31]
	v_mfma_f32_16x16x32_bf16 v[12:15], v[198:201], v[246:249], v[12:15]
	ds_read_b128 v[198:201], v178 offset:32768
	v_add_u32_e32 v178, v194, v197
	ds_read_b128 v[218:221], v178
	ds_read_b128 v[222:225], v178 offset:2048
	ds_read_b128 v[226:229], v178 offset:4096
	ds_read_b128 v[230:233], v178 offset:6144
	ds_read_b128 v[234:237], v178 offset:8192
	ds_read_b128 v[238:241], v178 offset:10240
	ds_read_b128 v[242:245], v178 offset:12288
	ds_read_b128 v[246:249], v178 offset:14336
	s_waitcnt lgkmcnt(7)
	v_mfma_f32_16x16x32_bf16 v[172:175], v[198:201], v[218:221], v[172:175]
	v_mfma_f32_16x16x32_bf16 v[168:171], v[202:205], v[218:221], v[168:171]
	v_mfma_f32_16x16x32_bf16 v[164:167], v[206:209], v[218:221], v[164:167]
	v_mfma_f32_16x16x32_bf16 v[160:163], v[210:213], v[218:221], v[160:163]
	s_waitcnt lgkmcnt(6)
	v_mfma_f32_16x16x32_bf16 v[156:159], v[198:201], v[222:225], v[156:159]
	v_mfma_f32_16x16x32_bf16 v[120:123], v[202:205], v[222:225], v[120:123]
	v_mfma_f32_16x16x32_bf16 v[100:103], v[206:209], v[222:225], v[100:103]
	v_mfma_f32_16x16x32_bf16 v[96:99], v[210:213], v[222:225], v[96:99]
	s_waitcnt lgkmcnt(5)
	v_mfma_f32_16x16x32_bf16 v[92:95], v[198:201], v[226:229], v[92:95]
	v_mfma_f32_16x16x32_bf16 v[88:91], v[202:205], v[226:229], v[88:91]
	v_mfma_f32_16x16x32_bf16 v[84:87], v[206:209], v[226:229], v[84:87]
	v_mfma_f32_16x16x32_bf16 v[80:83], v[210:213], v[226:229], v[80:83]
	s_waitcnt lgkmcnt(4)
	v_mfma_f32_16x16x32_bf16 v[76:79], v[198:201], v[230:233], v[76:79]
	v_mfma_f32_16x16x32_bf16 v[72:75], v[202:205], v[230:233], v[72:75]
	v_mfma_f32_16x16x32_bf16 v[68:71], v[206:209], v[230:233], v[68:71]
	v_mfma_f32_16x16x32_bf16 v[64:67], v[210:213], v[230:233], v[64:67]
	s_waitcnt lgkmcnt(3)
	v_mfma_f32_16x16x32_bf16 v[60:63], v[198:201], v[234:237], v[60:63]
	v_mfma_f32_16x16x32_bf16 v[56:59], v[202:205], v[234:237], v[56:59]
	v_mfma_f32_16x16x32_bf16 v[52:55], v[206:209], v[234:237], v[52:55]
	v_mfma_f32_16x16x32_bf16 v[48:51], v[210:213], v[234:237], v[48:51]
	s_waitcnt lgkmcnt(2)
	v_mfma_f32_16x16x32_bf16 v[44:47], v[198:201], v[238:241], v[44:47]
	v_mfma_f32_16x16x32_bf16 v[40:43], v[202:205], v[238:241], v[40:43]
	v_mfma_f32_16x16x32_bf16 v[36:39], v[206:209], v[238:241], v[36:39]
	v_mfma_f32_16x16x32_bf16 v[32:35], v[210:213], v[238:241], v[32:35]
	s_waitcnt lgkmcnt(1)
	v_mfma_f32_16x16x32_bf16 v[28:31], v[198:201], v[242:245], v[28:31]
	v_mfma_f32_16x16x32_bf16 v[24:27], v[202:205], v[242:245], v[24:27]
	v_mfma_f32_16x16x32_bf16 v[20:23], v[206:209], v[242:245], v[20:23]
	v_mfma_f32_16x16x32_bf16 v[16:19], v[210:213], v[242:245], v[16:19]
	s_waitcnt lgkmcnt(0)
	v_mfma_f32_16x16x32_bf16 v[12:15], v[198:201], v[246:249], v[12:15]
	v_mfma_f32_16x16x32_bf16 v[8:11], v[202:205], v[246:249], v[8:11]
	v_mfma_f32_16x16x32_bf16 v[4:7], v[206:209], v[246:249], v[4:7]
	v_mfma_f32_16x16x32_bf16 v[0:3], v[210:213], v[246:249], v[0:3]
	s_cbranch_scc0 .LBB0_953
; template <bool FP8>
; __device__ __forceinline__ void gemm_tile_256(const u16* __restrict__ A, int lda, const u16* __restrict__ Bt, int ldb,
;                                               int K, char* smem, f32x4 (&acc)[8][4]) {
;     ...
;   for (int kt = 0; kt < nk; ++kt) {
;     __syncthreads();
; #pragma unroll
;     for (int q = 0; q < 8; ++q) *(u32x4*)(smem + wofs + q * 4096) = ra[q];
; #pragma unroll
;     for (int q = 0; q < 4; ++q) *(u32x4*)(smem + 32768 + wofs + q * 4096) = rb[q];
;     __syncthreads();
;     if (kt + 1 < nk) {
;       const int k0 = (kt + 1) << 6;
; #pragma unroll
;       for (int q = 0; q < 8; ++q) ra[q] = *(const u32x4*)(ag + (size_t)q * 32 * lda + k0);
; #pragma unroll
;       for (int q = 0; q < 4; ++q) rb[q] = *(const u32x4*)(bg + (size_t)q * 32 * ldb + k0);
;     }
.LBB0_951:
	s_cmp_gt_u32 s7, 14
	s_setprio 0
	s_barrier
	s_waitcnt vmcnt(0)
	ds_write_b128 v195, v[104:107]
	ds_write_b128 v195, v[108:111] offset:4096
	ds_write_b128 v195, v[128:131] offset:8192
	ds_write_b128 v195, v[112:115] offset:12288
	ds_write_b128 v195, v[132:135] offset:16384
	ds_write_b128 v195, v[116:119] offset:20480
	ds_write_b128 v195, v[136:139] offset:24576
	ds_write_b128 v195, v[124:127] offset:28672
	ds_write_b128 v195, v[152:155] offset:32768
	ds_write_b128 v195, v[140:143] offset:36864
	ds_write_b128 v195, v[148:151] offset:40960
	ds_write_b128 v195, v[144:147] offset:45056
	s_waitcnt lgkmcnt(0)
	s_barrier
	s_cbranch_scc1 .LBB0_950
	v_lshl_add_u64 v[124:125], v[180:181], 0, s[10:11]
	v_add_co_u32_e32 v108, vcc, 0x10000, v124
	v_lshl_add_u64 v[144:145], v[182:183], 0, s[10:11]
	s_nop 0
	v_addc_co_u32_e32 v109, vcc, 0, v125, vcc
	v_add_co_u32_e32 v112, vcc, 0x20000, v124
	global_load_dwordx4 v[104:107], v[124:125], off offset:128
	s_nop 0
	global_load_dwordx4 v[108:111], v[108:109], off offset:128
	v_addc_co_u32_e32 v113, vcc, 0, v125, vcc
	v_add_co_u32_e32 v114, vcc, 0x30000, v124
	s_nop 1
	v_addc_co_u32_e32 v115, vcc, 0, v125, vcc
	v_add_co_u32_e32 v116, vcc, 0x40000, v124
	global_load_dwordx4 v[128:131], v[112:113], off offset:128
	s_nop 0
	global_load_dwordx4 v[112:115], v[114:115], off offset:128
	v_addc_co_u32_e32 v117, vcc, 0, v125, vcc
	v_add_co_u32_e32 v118, vcc, 0x50000, v124
	s_nop 1
	v_addc_co_u32_e32 v119, vcc, 0, v125, vcc
	v_add_co_u32_e32 v126, vcc, 0x60000, v124
	global_load_dwordx4 v[132:135], v[116:117], off offset:128
	s_nop 0
	global_load_dwordx4 v[116:119], v[118:119], off offset:128
	v_addc_co_u32_e32 v127, vcc, 0, v125, vcc
	v_add_co_u32_e32 v124, vcc, 0x70000, v124
	s_nop 1
	v_addc_co_u32_e32 v125, vcc, 0, v125, vcc
	v_add_co_u32_e32 v140, vcc, 0x10000, v144
	global_load_dwordx4 v[136:139], v[126:127], off offset:128
	s_nop 0
	global_load_dwordx4 v[124:127], v[124:125], off offset:128
	v_addc_co_u32_e32 v141, vcc, 0, v145, vcc
	v_add_co_u32_e32 v146, vcc, 0x20000, v144
	global_load_dwordx4 v[152:155], v[144:145], off offset:128
	s_nop 0
	global_load_dwordx4 v[140:143], v[140:141], off offset:128
	v_addc_co_u32_e32 v147, vcc, 0, v145, vcc
	v_add_co_u32_e32 v144, vcc, 0x30000, v144
	s_nop 1
	v_addc_co_u32_e32 v145, vcc, 0, v145, vcc
	global_load_dwordx4 v[148:151], v[146:147], off offset:128
	s_nop 0
	global_load_dwordx4 v[144:147], v[144:145], off offset:128
	s_branch .LBB0_950

; #define MFMA16(a, b, c) __builtin_amdgcn_mfma_f32_16x16x32_bf16(a, b, c, 0, 0, 0)
; #define MFMA8(a, b, c) __builtin_amdgcn_mfma_f32_16x16x32_fp8_fp8(a, b, c, 0, 0, 0)
; template <bool FP8>
; __device__ __forceinline__ void gemm_tile_256(const u16* __restrict__ A, int lda, const u16* __restrict__ Bt, int ldb,
;                                               int K, char* smem, f32x4 (&acc)[8][4]) {
;     ...
; #pragma unroll
;     for (int kk = 0; kk < 2; ++kk) {
;       const int ch = ((kk * 4 + fq) ^ sw) << 4;
;       bf16x8 bfr[4], af[8];
; #pragma unroll
;       for (int n = 0; n < 4; ++n) bfr[n] = *(const bf16x8*)(smem + brow + n * 2048 + ch);
; #pragma unroll
;       for (int m = 0; m < 8; ++m) af[m] = *(const bf16x8*)(smem + arow + m * 2048 + ch);
;       __builtin_amdgcn_sched_group_barrier(0x100, 12, 0);
;       __builtin_amdgcn_sched_group_barrier(0x008, 32, 0);
; #pragma unroll
;       for (int m = 0; m < 8; ++m)
; #pragma unroll
;         for (int n = 0; n < 4; ++n) {
;           if (FP8) {
;             union { bf16x8 v; long l[2]; } ua, ub;
;             ua.v = af[m]; ub.v = bfr[n];
;             acc[m][n] = MFMA8(ub.l[0], ua.l[0], acc[m][n]);
;             acc[m][n] = MFMA8(ub.l[1], ua.l[1], acc[m][n]);
;           } else {
;             acc[m][n] = MFMA16(bfr[n], af[m], acc[m][n]);
;           }
;         }
.LBB0_1032:
	s_setprio 2
	v_add_u32_e32 v178, v193, v196
	ds_read_b128 v[198:201], v178 offset:32768
	ds_read_b128 v[202:205], v178 offset:34816
	ds_read_b128 v[206:209], v178 offset:36864
	ds_read_b128 v[210:213], v178 offset:38912
	v_add_u32_e32 v178, v194, v196
	ds_read_b128 v[218:221], v178
	ds_read_b128 v[222:225], v178 offset:2048
	ds_read_b128 v[226:229], v178 offset:4096
	ds_read_b128 v[230:233], v178 offset:6144
	ds_read_b128 v[234:237], v178 offset:8192
	ds_read_b128 v[238:241], v178 offset:10240
	ds_read_b128 v[242:245], v178 offset:12288
	ds_read_b128 v[246:249], v178 offset:14336
	v_add_u32_e32 v178, v193, v197
	s_waitcnt lgkmcnt(7)
	v_mfma_f32_16x16x32_bf16 v[40:43], v[210:213], v[218:221], v[40:43]
	s_add_u32 s8, s8, 0x80
	s_addc_u32 s9, s9, 0
	s_add_i32 s0, s0, 1
	s_waitcnt lgkmcnt(6)
	v_mfma_f32_16x16x32_bf16 v[32:35], v[210:213], v[222:225], v[32:35]
	s_cmpk_lg_i32 s8, 0x1000
	s_waitcnt lgkmcnt(5)
	v_mfma_f32_16x16x32_bf16 v[24:27], v[210:213], v[226:229], v[24:27]
	s_waitcnt lgkmcnt(4)
	v_mfma_f32_16x16x32_bf16 v[16:19], v[210:213], v[230:233], v[16:19]
	s_waitcnt lgkmcnt(3)
	v_mfma_f32_16x16x32_bf16 v[12:15], v[210:213], v[234:237], v[12:15]
	s_waitcnt lgkmcnt(2)
	v_mfma_f32_16x16x32_bf16 v[8:11], v[210:213], v[238:241], v[8:11]
	s_waitcnt lgkmcnt(1)
	v_mfma_f32_16x16x32_bf16 v[4:7], v[210:213], v[242:245], v[4:7]
	s_waitcnt lgkmcnt(0)
	v_mfma_f32_16x16x32_bf16 v[0:3], v[210:213], v[246:249], v[0:3]
	ds_read_b128 v[210:213], v178 offset:38912
	v_mfma_f32_16x16x32_bf16 v[72:75], v[206:209], v[218:221], v[72:75]
	v_mfma_f32_16x16x32_bf16 v[64:67], v[206:209], v[222:225], v[64:67]
	v_mfma_f32_16x16x32_bf16 v[56:59], v[206:209], v[226:229], v[56:59]
	v_mfma_f32_16x16x32_bf16 v[48:51], v[206:209], v[230:233], v[48:51]
	v_mfma_f32_16x16x32_bf16 v[44:47], v[206:209], v[234:237], v[44:47]
	v_mfma_f32_16x16x32_bf16 v[36:39], v[206:209], v[238:241], v[36:39]
	v_mfma_f32_16x16x32_bf16 v[28:31], v[206:209], v[242:245], v[28:31]
	v_mfma_f32_16x16x32_bf16 v[20:23], v[206:209], v[246:249], v[20:23]
	ds_read_b128 v[206:209], v178 offset:36864
	v_mfma_f32_16x16x32_bf16 v[152:155], v[202:205], v[218:221], v[152:155]
	v_mfma_f32_16x16x32_bf16 v[140:143], v[202:205], v[222:225], v[140:143]
	v_mfma_f32_16x16x32_bf16 v[88:91], v[202:205], v[226:229], v[88:91]
	v_mfma_f32_16x16x32_bf16 v[80:83], v[202:205], v[230:233], v[80:83]
	v_mfma_f32_16x16x32_bf16 v[76:79], v[202:205], v[234:237], v[76:79]
	v_mfma_f32_16x16x32_bf16 v[68:71], v[202:205], v[238:241], v[68:71]
	v_mfma_f32_16x16x32_bf16 v[60:63], v[202:205], v[242:245], v[60:63]
	v_mfma_f32_16x16x32_bf16 v[52:55], v[202:205], v[246:249], v[52:55]
	ds_read_b128 v[202:205], v178 offset:34816
	v_mfma_f32_16x16x32_bf16 v[172:175], v[198:201], v[218:221], v[172:175]
	v_mfma_f32_16x16x32_bf16 v[168:171], v[198:201], v[222:225], v[168:171]
	v_mfma_f32_16x16x32_bf16 v[164:167], v[198:201], v[226:229], v[164:167]
	v_mfma_f32_16x16x32_bf16 v[160:163], v[198:201], v[230:233], v[160:163]
	v_mfma_f32_16x16x32_bf16 v[156:159], v[198:201], v[234:237], v[156:159]
	v_mfma_f32_16x16x32_bf16 v[144:147], v[198:201], v[238:241], v[144:147]
	v_mfma_f32_16x16x32_bf16 v[100:103], v[198:201], v[242:245], v[100:103]
	v_mfma_f32_16x16x32_bf16 v[84:87], v[198:201], v[246:249], v[84:87]
	ds_read_b128 v[198:201], v178 offset:32768
	v_add_u32_e32 v178, v194, v197
	ds_read_b128 v[218:221], v178
	ds_read_b128 v[222:225], v178 offset:2048
	ds_read_b128 v[226:229], v178 offset:4096
	ds_read_b128 v[230:233], v178 offset:6144
	ds_read_b128 v[234:237], v178 offset:8192
	ds_read_b128 v[238:241], v178 offset:10240
	ds_read_b128 v[242:245], v178 offset:12288
	ds_read_b128 v[246:249], v178 offset:14336
	s_waitcnt lgkmcnt(7)
	v_mfma_f32_16x16x32_bf16 v[172:175], v[198:201], v[218:221], v[172:175]
	v_mfma_f32_16x16x32_bf16 v[152:155], v[202:205], v[218:221], v[152:155]
	v_mfma_f32_16x16x32_bf16 v[72:75], v[206:209], v[218:221], v[72:75]
	v_mfma_f32_16x16x32_bf16 v[40:43], v[210:213], v[218:221], v[40:43]
	s_waitcnt lgkmcnt(6)
	v_mfma_f32_16x16x32_bf16 v[168:171], v[198:201], v[222:225], v[168:171]
	v_mfma_f32_16x16x32_bf16 v[140:143], v[202:205], v[222:225], v[140:143]
	v_mfma_f32_16x16x32_bf16 v[64:67], v[206:209], v[222:225], v[64:67]
	v_mfma_f32_16x16x32_bf16 v[32:35], v[210:213], v[222:225], v[32:35]
	s_waitcnt lgkmcnt(5)
	v_mfma_f32_16x16x32_bf16 v[164:167], v[198:201], v[226:229], v[164:167]
	v_mfma_f32_16x16x32_bf16 v[88:91], v[202:205], v[226:229], v[88:91]
	v_mfma_f32_16x16x32_bf16 v[56:59], v[206:209], v[226:229], v[56:59]
	v_mfma_f32_16x16x32_bf16 v[24:27], v[210:213], v[226:229], v[24:27]
	s_waitcnt lgkmcnt(4)
	v_mfma_f32_16x16x32_bf16 v[160:163], v[198:201], v[230:233], v[160:163]
	v_mfma_f32_16x16x32_bf16 v[80:83], v[202:205], v[230:233], v[80:83]
	v_mfma_f32_16x16x32_bf16 v[48:51], v[206:209], v[230:233], v[48:51]
	v_mfma_f32_16x16x32_bf16 v[16:19], v[210:213], v[230:233], v[16:19]
	s_waitcnt lgkmcnt(3)
	v_mfma_f32_16x16x32_bf16 v[156:159], v[198:201], v[234:237], v[156:159]
	v_mfma_f32_16x16x32_bf16 v[76:79], v[202:205], v[234:237], v[76:79]
	v_mfma_f32_16x16x32_bf16 v[44:47], v[206:209], v[234:237], v[44:47]
	v_mfma_f32_16x16x32_bf16 v[12:15], v[210:213], v[234:237], v[12:15]
	s_waitcnt lgkmcnt(2)
	v_mfma_f32_16x16x32_bf16 v[144:147], v[198:201], v[238:241], v[144:147]
	v_mfma_f32_16x16x32_bf16 v[68:71], v[202:205], v[238:241], v[68:71]
	v_mfma_f32_16x16x32_bf16 v[36:39], v[206:209], v[238:241], v[36:39]
	v_mfma_f32_16x16x32_bf16 v[8:11], v[210:213], v[238:241], v[8:11]
	s_waitcnt lgkmcnt(1)
	v_mfma_f32_16x16x32_bf16 v[100:103], v[198:201], v[242:245], v[100:103]
	v_mfma_f32_16x16x32_bf16 v[60:63], v[202:205], v[242:245], v[60:63]
	v_mfma_f32_16x16x32_bf16 v[28:31], v[206:209], v[242:245], v[28:31]
	v_mfma_f32_16x16x32_bf16 v[4:7], v[210:213], v[242:245], v[4:7]
	s_waitcnt lgkmcnt(0)
	v_mfma_f32_16x16x32_bf16 v[84:87], v[198:201], v[246:249], v[84:87]
	v_mfma_f32_16x16x32_bf16 v[52:55], v[202:205], v[246:249], v[52:55]
	v_mfma_f32_16x16x32_bf16 v[20:23], v[206:209], v[246:249], v[20:23]
	v_mfma_f32_16x16x32_bf16 v[0:3], v[210:213], v[246:249], v[0:3]
	s_cbranch_scc0 .LBB0_1030
; template <bool FP8>
; __device__ __forceinline__ void gemm_tile_256(const u16* __restrict__ A, int lda, const u16* __restrict__ Bt, int ldb,
;                                               int K, char* smem, f32x4 (&acc)[8][4]) {
;     ...
;   for (int kt = 0; kt < nk; ++kt) {
;     __syncthreads();
; #pragma unroll
;     for (int q = 0; q < 8; ++q) *(u32x4*)(smem + wofs + q * 4096) = ra[q];
; #pragma unroll
;     for (int q = 0; q < 4; ++q) *(u32x4*)(smem + 32768 + wofs + q * 4096) = rb[q];
;     __syncthreads();
;     if (kt + 1 < nk) {
;       const int k0 = (kt + 1) << 6;
; #pragma unroll
;       for (int q = 0; q < 8; ++q) ra[q] = *(const u32x4*)(ag + (size_t)q * 32 * lda + k0);
; #pragma unroll
;       for (int q = 0; q < 4; ++q) rb[q] = *(const u32x4*)(bg + (size_t)q * 32 * ldb + k0);
;     }
.LBB0_1033:
	s_cmp_gt_u32 s0, 30
	s_setprio 0
	s_barrier
	s_waitcnt vmcnt(0)
	ds_write_b128 v195, v[92:95]
	ds_write_b128 v195, v[96:99] offset:4096
	ds_write_b128 v195, v[116:119] offset:8192
	ds_write_b128 v195, v[104:107] offset:12288
	ds_write_b128 v195, v[120:123] offset:16384
	ds_write_b128 v195, v[108:111] offset:20480
	ds_write_b128 v195, v[124:127] offset:24576
	ds_write_b128 v195, v[112:115] offset:28672
	ds_write_b128 v195, v[148:151] offset:32768
	ds_write_b128 v195, v[128:131] offset:36864
	ds_write_b128 v195, v[136:139] offset:40960
	ds_write_b128 v195, v[132:135] offset:45056
	s_waitcnt lgkmcnt(0)
	s_barrier
	s_cbranch_scc1 .LBB0_1032
	v_lshl_add_u64 v[112:113], v[180:181], 0, s[8:9]
	v_add_co_u32_e32 v92, vcc, 0x1cc00000, v112
	v_lshl_add_u64 v[132:133], v[182:183], 0, s[8:9]
	s_nop 0
	v_addc_co_u32_e32 v93, vcc, 0, v113, vcc
	v_add_co_u32_e32 v96, vcc, 0x1cc20000, v112
	s_nop 1
	v_addc_co_u32_e32 v97, vcc, 0, v113, vcc
	v_add_co_u32_e32 v104, vcc, 0x1cc40000, v112
	global_load_dwordx4 v[92:95], v[92:93], off offset:128
	s_nop 0
	global_load_dwordx4 v[96:99], v[96:97], off offset:128
	v_addc_co_u32_e32 v105, vcc, 0, v113, vcc
	v_add_co_u32_e32 v106, vcc, 0x1cc60000, v112
	s_nop 1
	v_addc_co_u32_e32 v107, vcc, 0, v113, vcc
	v_add_co_u32_e32 v108, vcc, 0x1cc80000, v112
	global_load_dwordx4 v[116:119], v[104:105], off offset:128
	s_nop 0
	global_load_dwordx4 v[104:107], v[106:107], off offset:128
	v_addc_co_u32_e32 v109, vcc, 0, v113, vcc
	v_add_co_u32_e32 v110, vcc, 0x1cca0000, v112
	s_nop 1
	v_addc_co_u32_e32 v111, vcc, 0, v113, vcc
	v_add_co_u32_e32 v114, vcc, 0x1ccc0000, v112
	global_load_dwordx4 v[120:123], v[108:109], off offset:128
	s_nop 0
	global_load_dwordx4 v[108:111], v[110:111], off offset:128
	v_addc_co_u32_e32 v115, vcc, 0, v113, vcc
	v_add_co_u32_e32 v112, vcc, 0x1cce0000, v112
	s_nop 1
	v_addc_co_u32_e32 v113, vcc, 0, v113, vcc
	v_add_co_u32_e32 v128, vcc, 0x3880000, v132
	global_load_dwordx4 v[124:127], v[114:115], off offset:128
	s_nop 0
	global_load_dwordx4 v[112:115], v[112:113], off offset:128
	v_addc_co_u32_e32 v129, vcc, 0, v133, vcc
	v_add_co_u32_e32 v130, vcc, 0x38a0000, v132
	s_nop 1
	v_addc_co_u32_e32 v131, vcc, 0, v133, vcc
	v_add_co_u32_e32 v134, vcc, 0x38c0000, v132
	global_load_dwordx4 v[148:151], v[128:129], off offset:128
	s_nop 0
	global_load_dwordx4 v[128:131], v[130:131], off offset:128
	v_addc_co_u32_e32 v135, vcc, 0, v133, vcc
	v_add_co_u32_e32 v132, vcc, 0x38e0000, v132
	s_nop 1
	v_addc_co_u32_e32 v133, vcc, 0, v133, vcc
	global_load_dwordx4 v[136:139], v[134:135], off offset:128
	s_nop 0
	global_load_dwordx4 v[132:135], v[132:133], off offset:128
	s_branch .LBB0_1032

; #define MFMA16(a, b, c) __builtin_amdgcn_mfma_f32_16x16x32_bf16(a, b, c, 0, 0, 0)
; #define MFMA8(a, b, c) __builtin_amdgcn_mfma_f32_16x16x32_fp8_fp8(a, b, c, 0, 0, 0)
; template <bool FP8>
; __device__ __forceinline__ void gemm_tile_256(const u16* __restrict__ A, int lda, const u16* __restrict__ Bt, int ldb,
;                                               int K, char* smem, f32x4 (&acc)[8][4]) {
;     ...
; #pragma unroll
;     for (int kk = 0; kk < 2; ++kk) {
;       const int ch = ((kk * 4 + fq) ^ sw) << 4;
;       bf16x8 bfr[4], af[8];
; #pragma unroll
;       for (int n = 0; n < 4; ++n) bfr[n] = *(const bf16x8*)(smem + brow + n * 2048 + ch);
; #pragma unroll
;       for (int m = 0; m < 8; ++m) af[m] = *(const bf16x8*)(smem + arow + m * 2048 + ch);
;       __builtin_amdgcn_sched_group_barrier(0x100, 12, 0);
;       __builtin_amdgcn_sched_group_barrier(0x008, 32, 0);
; #pragma unroll
;       for (int m = 0; m < 8; ++m)
; #pragma unroll
;         for (int n = 0; n < 4; ++n) {
;           if (FP8) {
;             union { bf16x8 v; long l[2]; } ua, ub;
;             ua.v = af[m]; ub.v = bfr[n];
;             acc[m][n] = MFMA8(ub.l[0], ua.l[0], acc[m][n]);
;             acc[m][n] = MFMA8(ub.l[1], ua.l[1], acc[m][n]);
;           } else {
;             acc[m][n] = MFMA16(bfr[n], af[m], acc[m][n]);
;           }
;         }
.LBB0_1072:
	s_setprio 2
	v_add_u32_e32 v178, v193, v196
	ds_read_b128 v[198:201], v178 offset:32768
	ds_read_b128 v[202:205], v178 offset:34816
	ds_read_b128 v[206:209], v178 offset:36864
	ds_read_b128 v[210:213], v178 offset:38912
	v_add_u32_e32 v178, v194, v196
	ds_read_b128 v[218:221], v178
	ds_read_b128 v[222:225], v178 offset:2048
	ds_read_b128 v[226:229], v178 offset:4096
	ds_read_b128 v[230:233], v178 offset:6144
	ds_read_b128 v[234:237], v178 offset:8192
	ds_read_b128 v[238:241], v178 offset:10240
	ds_read_b128 v[242:245], v178 offset:12288
	ds_read_b128 v[246:249], v178 offset:14336
	v_add_u32_e32 v178, v193, v197
	s_waitcnt lgkmcnt(7)
	v_mfma_f32_16x16x32_bf16 v[160:163], v[210:213], v[218:221], v[160:163]
	s_add_u32 s18, s18, 0x80
	s_addc_u32 s19, s19, 0
	s_add_i32 s0, s0, 1
	s_waitcnt lgkmcnt(6)
	v_mfma_f32_16x16x32_bf16 v[144:147], v[210:213], v[222:225], v[144:147]
	s_cmpk_lg_i32 s18, 0x1000
	s_waitcnt lgkmcnt(5)
	v_mfma_f32_16x16x32_bf16 v[128:131], v[210:213], v[226:229], v[128:131]
	s_waitcnt lgkmcnt(4)
	v_mfma_f32_16x16x32_bf16 v[112:115], v[210:213], v[230:233], v[112:115]
	s_waitcnt lgkmcnt(3)
	v_mfma_f32_16x16x32_bf16 v[96:99], v[210:213], v[234:237], v[96:99]
	s_waitcnt lgkmcnt(2)
	v_mfma_f32_16x16x32_bf16 v[80:83], v[210:213], v[238:241], v[80:83]
	s_waitcnt lgkmcnt(1)
	v_mfma_f32_16x16x32_bf16 v[64:67], v[210:213], v[242:245], v[64:67]
	s_waitcnt lgkmcnt(0)
	v_mfma_f32_16x16x32_bf16 v[48:51], v[210:213], v[246:249], v[48:51]
	ds_read_b128 v[210:213], v178 offset:38912
	v_mfma_f32_16x16x32_bf16 v[164:167], v[206:209], v[218:221], v[164:167]
	v_mfma_f32_16x16x32_bf16 v[148:151], v[206:209], v[222:225], v[148:151]
	v_mfma_f32_16x16x32_bf16 v[132:135], v[206:209], v[226:229], v[132:135]
	v_mfma_f32_16x16x32_bf16 v[116:119], v[206:209], v[230:233], v[116:119]
	v_mfma_f32_16x16x32_bf16 v[100:103], v[206:209], v[234:237], v[100:103]
	v_mfma_f32_16x16x32_bf16 v[84:87], v[206:209], v[238:241], v[84:87]
	v_mfma_f32_16x16x32_bf16 v[68:71], v[206:209], v[242:245], v[68:71]
	v_mfma_f32_16x16x32_bf16 v[56:59], v[206:209], v[246:249], v[56:59]
	ds_read_b128 v[206:209], v178 offset:36864
	v_mfma_f32_16x16x32_bf16 v[168:171], v[202:205], v[218:221], v[168:171]
	v_mfma_f32_16x16x32_bf16 v[152:155], v[202:205], v[222:225], v[152:155]
	v_mfma_f32_16x16x32_bf16 v[136:139], v[202:205], v[226:229], v[136:139]
	v_mfma_f32_16x16x32_bf16 v[120:123], v[202:205], v[230:233], v[120:123]
	v_mfma_f32_16x16x32_bf16 v[104:107], v[202:205], v[234:237], v[104:107]
	v_mfma_f32_16x16x32_bf16 v[88:91], v[202:205], v[238:241], v[88:91]
	v_mfma_f32_16x16x32_bf16 v[72:75], v[202:205], v[242:245], v[72:75]
	v_mfma_f32_16x16x32_bf16 v[52:55], v[202:205], v[246:249], v[52:55]
	ds_read_b128 v[202:205], v178 offset:34816
	v_mfma_f32_16x16x32_bf16 v[172:175], v[198:201], v[218:221], v[172:175]
	v_mfma_f32_16x16x32_bf16 v[156:159], v[198:201], v[222:225], v[156:159]
	v_mfma_f32_16x16x32_bf16 v[140:143], v[198:201], v[226:229], v[140:143]
	v_mfma_f32_16x16x32_bf16 v[124:127], v[198:201], v[230:233], v[124:127]
	v_mfma_f32_16x16x32_bf16 v[108:111], v[198:201], v[234:237], v[108:111]
	v_mfma_f32_16x16x32_bf16 v[92:95], v[198:201], v[238:241], v[92:95]
	v_mfma_f32_16x16x32_bf16 v[76:79], v[198:201], v[242:245], v[76:79]
	v_mfma_f32_16x16x32_bf16 v[60:63], v[198:201], v[246:249], v[60:63]
	ds_read_b128 v[198:201], v178 offset:32768
	v_add_u32_e32 v178, v194, v197
	ds_read_b128 v[218:221], v178
	ds_read_b128 v[222:225], v178 offset:2048
	ds_read_b128 v[226:229], v178 offset:4096
	ds_read_b128 v[230:233], v178 offset:6144
	ds_read_b128 v[234:237], v178 offset:8192
	ds_read_b128 v[238:241], v178 offset:10240
	ds_read_b128 v[242:245], v178 offset:12288
	ds_read_b128 v[246:249], v178 offset:14336
	s_waitcnt lgkmcnt(7)
	v_mfma_f32_16x16x32_bf16 v[172:175], v[198:201], v[218:221], v[172:175]
	v_mfma_f32_16x16x32_bf16 v[168:171], v[202:205], v[218:221], v[168:171]
	v_mfma_f32_16x16x32_bf16 v[164:167], v[206:209], v[218:221], v[164:167]
	v_mfma_f32_16x16x32_bf16 v[160:163], v[210:213], v[218:221], v[160:163]
	s_waitcnt lgkmcnt(6)
	v_mfma_f32_16x16x32_bf16 v[156:159], v[198:201], v[222:225], v[156:159]
	v_mfma_f32_16x16x32_bf16 v[152:155], v[202:205], v[222:225], v[152:155]
	v_mfma_f32_16x16x32_bf16 v[148:151], v[206:209], v[222:225], v[148:151]
	v_mfma_f32_16x16x32_bf16 v[144:147], v[210:213], v[222:225], v[144:147]
	s_waitcnt lgkmcnt(5)
	v_mfma_f32_16x16x32_bf16 v[140:143], v[198:201], v[226:229], v[140:143]
	v_mfma_f32_16x16x32_bf16 v[136:139], v[202:205], v[226:229], v[136:139]
	v_mfma_f32_16x16x32_bf16 v[132:135], v[206:209], v[226:229], v[132:135]
	v_mfma_f32_16x16x32_bf16 v[128:131], v[210:213], v[226:229], v[128:131]
	s_waitcnt lgkmcnt(4)
	v_mfma_f32_16x16x32_bf16 v[124:127], v[198:201], v[230:233], v[124:127]
	v_mfma_f32_16x16x32_bf16 v[120:123], v[202:205], v[230:233], v[120:123]
	v_mfma_f32_16x16x32_bf16 v[116:119], v[206:209], v[230:233], v[116:119]
	v_mfma_f32_16x16x32_bf16 v[112:115], v[210:213], v[230:233], v[112:115]
	s_waitcnt lgkmcnt(3)
	v_mfma_f32_16x16x32_bf16 v[108:111], v[198:201], v[234:237], v[108:111]
	v_mfma_f32_16x16x32_bf16 v[104:107], v[202:205], v[234:237], v[104:107]
	v_mfma_f32_16x16x32_bf16 v[100:103], v[206:209], v[234:237], v[100:103]
	v_mfma_f32_16x16x32_bf16 v[96:99], v[210:213], v[234:237], v[96:99]
	s_waitcnt lgkmcnt(2)
	v_mfma_f32_16x16x32_bf16 v[92:95], v[198:201], v[238:241], v[92:95]
	v_mfma_f32_16x16x32_bf16 v[88:91], v[202:205], v[238:241], v[88:91]
	v_mfma_f32_16x16x32_bf16 v[84:87], v[206:209], v[238:241], v[84:87]
	v_mfma_f32_16x16x32_bf16 v[80:83], v[210:213], v[238:241], v[80:83]
	s_waitcnt lgkmcnt(1)
	v_mfma_f32_16x16x32_bf16 v[76:79], v[198:201], v[242:245], v[76:79]
	v_mfma_f32_16x16x32_bf16 v[72:75], v[202:205], v[242:245], v[72:75]
	v_mfma_f32_16x16x32_bf16 v[68:71], v[206:209], v[242:245], v[68:71]
	v_mfma_f32_16x16x32_bf16 v[64:67], v[210:213], v[242:245], v[64:67]
	s_waitcnt lgkmcnt(0)
	v_mfma_f32_16x16x32_bf16 v[60:63], v[198:201], v[246:249], v[60:63]
	v_mfma_f32_16x16x32_bf16 v[52:55], v[202:205], v[246:249], v[52:55]
	v_mfma_f32_16x16x32_bf16 v[56:59], v[206:209], v[246:249], v[56:59]
	v_mfma_f32_16x16x32_bf16 v[48:51], v[210:213], v[246:249], v[48:51]
	s_cbranch_scc0 .LBB0_1070
; template <bool FP8>
; __device__ __forceinline__ void gemm_tile_256(const u16* __restrict__ A, int lda, const u16* __restrict__ Bt, int ldb,
;                                               int K, char* smem, f32x4 (&acc)[8][4]) {
;     ...
;   for (int kt = 0; kt < nk; ++kt) {
;     __syncthreads();
; #pragma unroll
;     for (int q = 0; q < 8; ++q) *(u32x4*)(smem + wofs + q * 4096) = ra[q];
; #pragma unroll
;     for (int q = 0; q < 4; ++q) *(u32x4*)(smem + 32768 + wofs + q * 4096) = rb[q];
;     __syncthreads();
;     if (kt + 1 < nk) {
;       const int k0 = (kt + 1) << 6;
; #pragma unroll
;       for (int q = 0; q < 8; ++q) ra[q] = *(const u32x4*)(ag + (size_t)q * 32 * lda + k0);
; #pragma unroll
;       for (int q = 0; q < 4; ++q) rb[q] = *(const u32x4*)(bg + (size_t)q * 32 * ldb + k0);
;     }
.LBB0_1073:
	s_cmp_gt_u32 s0, 30
	s_setprio 0
	s_barrier
	s_waitcnt vmcnt(0)
	ds_write_b128 v195, v[0:3]
	ds_write_b128 v195, v[4:7] offset:4096
	ds_write_b128 v195, v[20:23] offset:8192
	ds_write_b128 v195, v[8:11] offset:12288
	ds_write_b128 v195, v[24:27] offset:16384
	ds_write_b128 v195, v[12:15] offset:20480
	ds_write_b128 v195, v[28:31] offset:24576
	ds_write_b128 v195, v[16:19] offset:28672
	ds_write_b128 v195, v[44:47] offset:32768
	ds_write_b128 v195, v[32:35] offset:36864
	ds_write_b128 v195, v[40:43] offset:40960
	ds_write_b128 v195, v[36:39] offset:45056
	s_waitcnt lgkmcnt(0)
	s_barrier
	s_cbranch_scc1 .LBB0_1072
	v_lshl_add_u64 v[16:17], v[180:181], 0, s[18:19]
	v_add_co_u32_e32 v0, vcc, 0x4c00000, v16
	v_lshl_add_u64 v[36:37], v[182:183], 0, s[18:19]
	s_nop 0
	v_addc_co_u32_e32 v1, vcc, 0, v17, vcc
	v_add_co_u32_e32 v4, vcc, 0x4c20000, v16
	s_nop 1
	v_addc_co_u32_e32 v5, vcc, 0, v17, vcc
	v_add_co_u32_e32 v8, vcc, 0x4c40000, v16
	global_load_dwordx4 v[0:3], v[0:1], off offset:128
	s_nop 0
	global_load_dwordx4 v[4:7], v[4:5], off offset:128
	v_addc_co_u32_e32 v9, vcc, 0, v17, vcc
	v_add_co_u32_e32 v10, vcc, 0x4c60000, v16
	s_nop 1
	v_addc_co_u32_e32 v11, vcc, 0, v17, vcc
	v_add_co_u32_e32 v12, vcc, 0x4c80000, v16
	global_load_dwordx4 v[20:23], v[8:9], off offset:128
	s_nop 0
	global_load_dwordx4 v[8:11], v[10:11], off offset:128
	v_addc_co_u32_e32 v13, vcc, 0, v17, vcc
	v_add_co_u32_e32 v14, vcc, 0x4ca0000, v16
	s_nop 1
	v_addc_co_u32_e32 v15, vcc, 0, v17, vcc
	v_add_co_u32_e32 v18, vcc, 0x4cc0000, v16
	global_load_dwordx4 v[24:27], v[12:13], off offset:128
	s_nop 0
	global_load_dwordx4 v[12:15], v[14:15], off offset:128
	v_addc_co_u32_e32 v19, vcc, 0, v17, vcc
	v_add_co_u32_e32 v16, vcc, 0x4ce0000, v16
	s_nop 1
	v_addc_co_u32_e32 v17, vcc, 0, v17, vcc
	v_add_co_u32_e32 v32, vcc, 0x4080000, v36
	global_load_dwordx4 v[28:31], v[18:19], off offset:128
	s_nop 0
	global_load_dwordx4 v[16:19], v[16:17], off offset:128
	v_addc_co_u32_e32 v33, vcc, 0, v37, vcc
	v_add_co_u32_e32 v34, vcc, 0x40a0000, v36
	s_nop 1
	v_addc_co_u32_e32 v35, vcc, 0, v37, vcc
	v_add_co_u32_e32 v38, vcc, 0x40c0000, v36
	global_load_dwordx4 v[44:47], v[32:33], off offset:128
	s_nop 0
	global_load_dwordx4 v[32:35], v[34:35], off offset:128
	v_addc_co_u32_e32 v39, vcc, 0, v37, vcc
	v_add_co_u32_e32 v36, vcc, 0x40e0000, v36
	s_nop 1
	v_addc_co_u32_e32 v37, vcc, 0, v37, vcc
	global_load_dwordx4 v[40:43], v[38:39], off offset:128
	s_nop 0
	global_load_dwordx4 v[36:39], v[36:37], off offset:128
	s_branch .LBB0_1072
